# attention block epilogue: lane^1 exchange via DPP quad_perm instead of ds_bpermute round trips (64 per block)
# baseline (speedup 1.0000x reference)
; __device__ __forceinline__ int crow(int r, int hi) { return (r & 3) + 8 * (r >> 2) + 4 * hi; }
; __device__ __forceinline__ void attn2_block(const Block2& B, char* lds) {
;     ...
;     if (hi == 0) li_l[r32] = l_reg; asm volatile("s_waitcnt lgkmcnt(0)" ::: "memory");
;     float rli[16];
; #pragma unroll
;     for (int r = 0; r < 16; ++r) rli[r] = __builtin_amdgcn_rcpf(li_l[crow(r, hi)]);
;     bf16* Ow = (kh == 0 ? B.O0 : B.O1) + (size_t)(pr * 32) * D;
; #pragma unroll
;     for (int r = 0; r < 16; ++r) { const int orow = crow(r, hi);
; #pragma unroll
;         for (int d0 = 0; d0 < 4; ++d0) { const float v = o[d0][r] * rli[r]; const float vn = __shfl_xor(v, 1);
;             if ((r32 & 1) == 0) *(unsigned*)(Ow + (size_t)orow * D + d0 * 32 + r32) = cvtpk(v, vn); } }
.LBB0_410:
	s_or_b64 exec, exec, s[4:5]
	s_waitcnt lgkmcnt(0)
	v_add_u32_e32 v0, s52, v196
	s_lshl_b32 s2, s14, 1
	ds_read_b128 v[12:15], v0
	ds_read_b128 v[8:11], v0 offset:32
	s_ashr_i32 s3, s2, 31
	s_lshl_b64 s[2:3], s[2:3], 21
	s_add_u32 s2, s64, s2
	s_addc_u32 s3, s65, s3
	s_add_u32 s4, s2, s15
	s_waitcnt lgkmcnt(1)
	v_rcp_f32_e32 v18, v12
	v_and_b32_e32 v12, 64, v207
	s_addc_u32 s5, s3, 0
	v_xor_b32_e32 v16, 1, v207
	v_add_u32_e32 v12, 64, v12
	s_and_b64 s[2:3], s[16:17], exec
	v_cmp_lt_i32_e32 vcc, v16, v12
	s_cselect_b32 s2, 0, 0x200000
	s_add_u32 s2, s4, s2
	v_cndmask_b32_e32 v16, v207, v16, vcc
	v_lshlrev_b32_e32 v26, 2, v16
	v_mul_f32_e32 v19, v64, v18
	ds_read_b128 v[4:7], v0 offset:64
	ds_read_b128 v[0:3], v0 offset:96
	s_addc_u32 s3, s5, 0
	s_lshl_b32 s4, s83, 13
	s_nop 1
	v_mov_b32_dpp v20, v19 quad_perm:[1,0,3,2] row_mask:0xf bank_mask:0xf
	s_add_u32 s4, s2, s4
	s_addc_u32 s5, s3, 0
	v_and_b32_e32 v16, 1, v208
	v_lshlrev_b32_e32 v194, 1, v189
	v_cmp_eq_u32_e64 s[2:3], 0, v16
	v_lshlrev_b32_e32 v16, 10, v209
	v_lshl_add_u64 v[22:23], s[4:5], 0, v[194:195]
	v_mov_b32_e32 v17, v195
	v_lshl_add_u64 v[16:17], v[22:23], 0, v[16:17]
	s_and_saveexec_b64 s[4:5], s[2:3]
	s_cbranch_execz .LBB0_412
	s_waitcnt lgkmcnt(0)
	v_cvt_pk_bf16_f32 v19, v19, v20
	global_store_dword v[16:17], v19, off
.LBB0_412:
	s_or_b64 exec, exec, s[4:5]
	v_mul_f32_e32 v19, v80, v18
	s_waitcnt lgkmcnt(0)
	s_nop 1
	v_mov_b32_dpp v20, v19 quad_perm:[1,0,3,2] row_mask:0xf bank_mask:0xf
	s_and_saveexec_b64 s[4:5], s[2:3]
	s_cbranch_execz .LBB0_414
	s_waitcnt lgkmcnt(0)
	v_cvt_pk_bf16_f32 v19, v19, v20
	global_store_dword v[16:17], v19, off offset:64
.LBB0_414:
	s_or_b64 exec, exec, s[4:5]
	v_mul_f32_e32 v19, v96, v18
	s_waitcnt lgkmcnt(0)
	s_nop 1
	v_mov_b32_dpp v20, v19 quad_perm:[1,0,3,2] row_mask:0xf bank_mask:0xf
	s_and_saveexec_b64 s[4:5], s[2:3]
	s_cbranch_execz .LBB0_416
	s_waitcnt lgkmcnt(0)
	v_cvt_pk_bf16_f32 v19, v19, v20
	global_store_dword v[16:17], v19, off offset:128
.LBB0_416:
	s_or_b64 exec, exec, s[4:5]
	v_mul_f32_e32 v18, v112, v18
	s_nop 1
	v_mov_b32_dpp v19, v18 quad_perm:[1,0,3,2] row_mask:0xf bank_mask:0xf
	s_and_saveexec_b64 s[4:5], s[2:3]
	s_cbranch_execz .LBB0_418
	s_waitcnt lgkmcnt(0)
	v_cvt_pk_bf16_f32 v18, v18, v19
	global_store_dword v[16:17], v18, off offset:192
.LBB0_418:
	s_or_b64 exec, exec, s[4:5]
	v_rcp_f32_e32 v13, v13
	s_nop 0
	v_mul_f32_e32 v18, v65, v13
	s_waitcnt lgkmcnt(0)
	s_nop 1
	v_mov_b32_dpp v19, v18 quad_perm:[1,0,3,2] row_mask:0xf bank_mask:0xf
	s_and_saveexec_b64 s[4:5], s[2:3]
	s_cbranch_execz .LBB0_420
	s_waitcnt lgkmcnt(0)
	v_cvt_pk_bf16_f32 v18, v18, v19
	global_store_dword v[16:17], v18, off offset:256
.LBB0_420:
	s_or_b64 exec, exec, s[4:5]
	v_mul_f32_e32 v18, v81, v13
	s_waitcnt lgkmcnt(0)
	s_nop 1
	v_mov_b32_dpp v19, v18 quad_perm:[1,0,3,2] row_mask:0xf bank_mask:0xf
	s_and_saveexec_b64 s[4:5], s[2:3]
	s_cbranch_execz .LBB0_422
	s_waitcnt lgkmcnt(0)
	v_cvt_pk_bf16_f32 v18, v18, v19
	global_store_dword v[16:17], v18, off offset:320
.LBB0_422:
	s_or_b64 exec, exec, s[4:5]
	v_mul_f32_e32 v18, v97, v13
	s_waitcnt lgkmcnt(0)
	s_nop 1
	v_mov_b32_dpp v19, v18 quad_perm:[1,0,3,2] row_mask:0xf bank_mask:0xf
	s_and_saveexec_b64 s[4:5], s[2:3]
	s_cbranch_execz .LBB0_424
	s_waitcnt lgkmcnt(0)
	v_cvt_pk_bf16_f32 v18, v18, v19
	global_store_dword v[16:17], v18, off offset:384
.LBB0_424:
	s_or_b64 exec, exec, s[4:5]
	v_mul_f32_e32 v13, v113, v13
	s_nop 1
	v_mov_b32_dpp v18, v13 quad_perm:[1,0,3,2] row_mask:0xf bank_mask:0xf
	s_and_saveexec_b64 s[4:5], s[2:3]
	s_cbranch_execz .LBB0_426
	s_waitcnt lgkmcnt(0)
	v_cvt_pk_bf16_f32 v13, v13, v18
	global_store_dword v[16:17], v13, off offset:448
.LBB0_426:
	s_or_b64 exec, exec, s[4:5]
	v_rcp_f32_e32 v13, v14
	s_nop 0
	v_mul_f32_e32 v14, v66, v13
	s_waitcnt lgkmcnt(0)
	s_nop 1
	v_mov_b32_dpp v18, v14 quad_perm:[1,0,3,2] row_mask:0xf bank_mask:0xf
	s_and_saveexec_b64 s[4:5], s[2:3]
	s_cbranch_execz .LBB0_428
	s_waitcnt lgkmcnt(0)
	v_cvt_pk_bf16_f32 v14, v14, v18
	global_store_dword v[16:17], v14, off offset:512
.LBB0_428:
	s_or_b64 exec, exec, s[4:5]
	v_mul_f32_e32 v14, v82, v13
	s_waitcnt lgkmcnt(0)
	s_nop 1
	v_mov_b32_dpp v18, v14 quad_perm:[1,0,3,2] row_mask:0xf bank_mask:0xf
	s_and_saveexec_b64 s[4:5], s[2:3]
	s_cbranch_execz .LBB0_430
	s_waitcnt lgkmcnt(0)
	v_cvt_pk_bf16_f32 v14, v14, v18
	global_store_dword v[16:17], v14, off offset:576
.LBB0_430:
	s_or_b64 exec, exec, s[4:5]
	v_mul_f32_e32 v14, v98, v13
	s_waitcnt lgkmcnt(0)
	s_nop 1
	v_mov_b32_dpp v18, v14 quad_perm:[1,0,3,2] row_mask:0xf bank_mask:0xf
	s_and_saveexec_b64 s[4:5], s[2:3]
	s_cbranch_execz .LBB0_432
	s_waitcnt lgkmcnt(0)
	v_cvt_pk_bf16_f32 v14, v14, v18
	global_store_dword v[16:17], v14, off offset:640
.LBB0_432:
	s_or_b64 exec, exec, s[4:5]
	v_mul_f32_e32 v13, v114, v13
	s_nop 1
	v_mov_b32_dpp v14, v13 quad_perm:[1,0,3,2] row_mask:0xf bank_mask:0xf
	s_and_saveexec_b64 s[4:5], s[2:3]
	s_cbranch_execz .LBB0_434
	s_waitcnt lgkmcnt(0)
	v_cvt_pk_bf16_f32 v13, v13, v14
	global_store_dword v[16:17], v13, off offset:704
.LBB0_434:
	s_or_b64 exec, exec, s[4:5]
	v_rcp_f32_e32 v13, v15
	s_waitcnt lgkmcnt(0)
	v_mul_f32_e32 v14, v67, v13
	s_nop 1
	v_mov_b32_dpp v15, v14 quad_perm:[1,0,3,2] row_mask:0xf bank_mask:0xf
	s_and_saveexec_b64 s[4:5], s[2:3]
	s_cbranch_execz .LBB0_436
	s_waitcnt lgkmcnt(0)
	v_cvt_pk_bf16_f32 v14, v14, v15
	global_store_dword v[16:17], v14, off offset:768
.LBB0_436:
	s_or_b64 exec, exec, s[4:5]
	v_mul_f32_e32 v14, v83, v13
	s_waitcnt lgkmcnt(0)
	s_nop 1
	v_mov_b32_dpp v15, v14 quad_perm:[1,0,3,2] row_mask:0xf bank_mask:0xf
	s_and_saveexec_b64 s[4:5], s[2:3]
	s_cbranch_execz .LBB0_438
	s_waitcnt lgkmcnt(0)
	v_cvt_pk_bf16_f32 v14, v14, v15
	global_store_dword v[16:17], v14, off offset:832
; __device__ __forceinline__ int crow(int r, int hi) { return (r & 3) + 8 * (r >> 2) + 4 * hi; }
; __device__ __forceinline__ void attn2_block(const Block2& B, char* lds) {
;     ...
;     for (int r = 0; r < 16; ++r) { const int orow = crow(r, hi);
; #pragma unroll
;         for (int d0 = 0; d0 < 4; ++d0) { const float v = o[d0][r] * rli[r]; const float vn = __shfl_xor(v, 1);
;             if ((r32 & 1) == 0) *(unsigned*)(Ow + (size_t)orow * D + d0 * 32 + r32) = cvtpk(v, vn); } }
.LBB0_438:
	s_or_b64 exec, exec, s[4:5]
	v_mul_f32_e32 v14, v99, v13
	s_waitcnt lgkmcnt(0)
	s_nop 1
	v_mov_b32_dpp v15, v14 quad_perm:[1,0,3,2] row_mask:0xf bank_mask:0xf
	s_and_saveexec_b64 s[4:5], s[2:3]
	s_cbranch_execz .LBB0_440
	s_waitcnt lgkmcnt(0)
	v_cvt_pk_bf16_f32 v14, v14, v15
	global_store_dword v[16:17], v14, off offset:896
.LBB0_440:
	s_or_b64 exec, exec, s[4:5]
	v_mul_f32_e32 v13, v115, v13
	s_nop 1
	v_mov_b32_dpp v14, v13 quad_perm:[1,0,3,2] row_mask:0xf bank_mask:0xf
	s_and_saveexec_b64 s[4:5], s[2:3]
	s_cbranch_execz .LBB0_442
	s_waitcnt lgkmcnt(0)
	v_cvt_pk_bf16_f32 v13, v13, v14
	global_store_dword v[16:17], v13, off offset:960
.LBB0_442:
	s_or_b64 exec, exec, s[4:5]
	v_rcp_f32_e32 v8, v8
	s_nop 0
	v_mul_f32_e32 v13, v68, v8
	s_waitcnt lgkmcnt(0)
	s_nop 1
	v_mov_b32_dpp v14, v13 quad_perm:[1,0,3,2] row_mask:0xf bank_mask:0xf
	s_and_saveexec_b64 s[4:5], s[2:3]
	s_cbranch_execz .LBB0_444
	s_waitcnt lgkmcnt(0)
	v_cvt_pk_bf16_f32 v13, v13, v14
	global_store_dword v[16:17], v13, off offset:2048
.LBB0_444:
	s_or_b64 exec, exec, s[4:5]
	v_mul_f32_e32 v13, v84, v8
	s_waitcnt lgkmcnt(0)
	s_nop 1
	v_mov_b32_dpp v14, v13 quad_perm:[1,0,3,2] row_mask:0xf bank_mask:0xf
	s_and_saveexec_b64 s[4:5], s[2:3]
	s_cbranch_execz .LBB0_446
	s_waitcnt lgkmcnt(0)
	v_cvt_pk_bf16_f32 v13, v13, v14
	global_store_dword v[16:17], v13, off offset:2112
.LBB0_446:
	s_or_b64 exec, exec, s[4:5]
	v_mul_f32_e32 v13, v100, v8
	s_waitcnt lgkmcnt(0)
	s_nop 1
	v_mov_b32_dpp v14, v13 quad_perm:[1,0,3,2] row_mask:0xf bank_mask:0xf
	s_and_saveexec_b64 s[4:5], s[2:3]
	s_cbranch_execz .LBB0_448
	s_waitcnt lgkmcnt(0)
	v_cvt_pk_bf16_f32 v13, v13, v14
	global_store_dword v[16:17], v13, off offset:2176
.LBB0_448:
	s_or_b64 exec, exec, s[4:5]
	v_mul_f32_e32 v8, v116, v8
	s_nop 1
	v_mov_b32_dpp v13, v8 quad_perm:[1,0,3,2] row_mask:0xf bank_mask:0xf
	s_and_saveexec_b64 s[4:5], s[2:3]
	s_cbranch_execz .LBB0_450
	s_waitcnt lgkmcnt(0)
	v_cvt_pk_bf16_f32 v8, v8, v13
	global_store_dword v[16:17], v8, off offset:2240
.LBB0_450:
	s_or_b64 exec, exec, s[4:5]
	v_rcp_f32_e32 v8, v9
	s_nop 0
	v_mul_f32_e32 v9, v69, v8
	s_waitcnt lgkmcnt(0)
	s_nop 1
	v_mov_b32_dpp v13, v9 quad_perm:[1,0,3,2] row_mask:0xf bank_mask:0xf
	s_and_saveexec_b64 s[4:5], s[2:3]
	s_cbranch_execz .LBB0_452
	s_waitcnt lgkmcnt(0)
	v_cvt_pk_bf16_f32 v9, v9, v13
	global_store_dword v[16:17], v9, off offset:2304
.LBB0_452:
	s_or_b64 exec, exec, s[4:5]
	v_mul_f32_e32 v9, v85, v8
	s_waitcnt lgkmcnt(0)
	s_nop 1
	v_mov_b32_dpp v13, v9 quad_perm:[1,0,3,2] row_mask:0xf bank_mask:0xf
	s_and_saveexec_b64 s[4:5], s[2:3]
	s_cbranch_execz .LBB0_454
	s_waitcnt lgkmcnt(0)
	v_cvt_pk_bf16_f32 v9, v9, v13
	global_store_dword v[16:17], v9, off offset:2368
.LBB0_454:
	s_or_b64 exec, exec, s[4:5]
	v_mul_f32_e32 v9, v101, v8
	s_waitcnt lgkmcnt(0)
	s_nop 1
	v_mov_b32_dpp v13, v9 quad_perm:[1,0,3,2] row_mask:0xf bank_mask:0xf
	s_and_saveexec_b64 s[4:5], s[2:3]
	s_cbranch_execz .LBB0_456
	s_waitcnt lgkmcnt(0)
	v_cvt_pk_bf16_f32 v9, v9, v13
	global_store_dword v[16:17], v9, off offset:2432
.LBB0_456:
	s_or_b64 exec, exec, s[4:5]
	v_mul_f32_e32 v8, v117, v8
	s_nop 1
	v_mov_b32_dpp v9, v8 quad_perm:[1,0,3,2] row_mask:0xf bank_mask:0xf
	s_and_saveexec_b64 s[4:5], s[2:3]
	s_cbranch_execz .LBB0_458
	s_waitcnt lgkmcnt(0)
	v_cvt_pk_bf16_f32 v8, v8, v9
	global_store_dword v[16:17], v8, off offset:2496
.LBB0_458:
	s_or_b64 exec, exec, s[4:5]
	v_rcp_f32_e32 v8, v10
	s_waitcnt lgkmcnt(0)
	v_mul_f32_e32 v9, v70, v8
	s_nop 1
	v_mov_b32_dpp v10, v9 quad_perm:[1,0,3,2] row_mask:0xf bank_mask:0xf
	s_and_saveexec_b64 s[4:5], s[2:3]
	s_cbranch_execz .LBB0_460
	s_waitcnt lgkmcnt(0)
	v_cvt_pk_bf16_f32 v9, v9, v10
	global_store_dword v[16:17], v9, off offset:2560
.LBB0_460:
	s_or_b64 exec, exec, s[4:5]
	v_mul_f32_e32 v9, v86, v8
	s_waitcnt lgkmcnt(0)
	s_nop 1
	v_mov_b32_dpp v10, v9 quad_perm:[1,0,3,2] row_mask:0xf bank_mask:0xf
	s_and_saveexec_b64 s[4:5], s[2:3]
	s_cbranch_execz .LBB0_462
	s_waitcnt lgkmcnt(0)
	v_cvt_pk_bf16_f32 v9, v9, v10
	global_store_dword v[16:17], v9, off offset:2624
.LBB0_462:
	s_or_b64 exec, exec, s[4:5]
	v_mul_f32_e32 v9, v102, v8
	s_waitcnt lgkmcnt(0)
	s_nop 1
	v_mov_b32_dpp v10, v9 quad_perm:[1,0,3,2] row_mask:0xf bank_mask:0xf
	s_and_saveexec_b64 s[4:5], s[2:3]
	s_cbranch_execz .LBB0_464
	s_waitcnt lgkmcnt(0)
	v_cvt_pk_bf16_f32 v9, v9, v10
	global_store_dword v[16:17], v9, off offset:2688
.LBB0_464:
	s_or_b64 exec, exec, s[4:5]
	v_mul_f32_e32 v8, v118, v8
	s_nop 1
	v_mov_b32_dpp v9, v8 quad_perm:[1,0,3,2] row_mask:0xf bank_mask:0xf
	s_and_saveexec_b64 s[4:5], s[2:3]
	s_cbranch_execz .LBB0_466
	s_waitcnt lgkmcnt(0)
	v_cvt_pk_bf16_f32 v8, v8, v9
	global_store_dword v[16:17], v8, off offset:2752
.LBB0_466:
	s_or_b64 exec, exec, s[4:5]
	v_rcp_f32_e32 v8, v11
	s_waitcnt lgkmcnt(0)
	v_mul_f32_e32 v9, v71, v8
	s_nop 1
	v_mov_b32_dpp v10, v9 quad_perm:[1,0,3,2] row_mask:0xf bank_mask:0xf
	s_and_saveexec_b64 s[4:5], s[2:3]
	s_cbranch_execz .LBB0_468
	s_waitcnt lgkmcnt(0)
	v_cvt_pk_bf16_f32 v9, v9, v10
	global_store_dword v[16:17], v9, off offset:2816
.LBB0_468:
	s_or_b64 exec, exec, s[4:5]
	v_mul_f32_e32 v9, v87, v8
	s_waitcnt lgkmcnt(0)
	s_nop 1
	v_mov_b32_dpp v10, v9 quad_perm:[1,0,3,2] row_mask:0xf bank_mask:0xf
	s_and_saveexec_b64 s[4:5], s[2:3]
	s_cbranch_execz .LBB0_470
	s_waitcnt lgkmcnt(0)
	v_cvt_pk_bf16_f32 v9, v9, v10
	global_store_dword v[16:17], v9, off offset:2880
.LBB0_470:
	s_or_b64 exec, exec, s[4:5]
	v_mul_f32_e32 v9, v103, v8
	s_waitcnt lgkmcnt(0)
	s_nop 1
	v_mov_b32_dpp v10, v9 quad_perm:[1,0,3,2] row_mask:0xf bank_mask:0xf
	s_and_saveexec_b64 s[4:5], s[2:3]
	s_cbranch_execz .LBB0_472
	s_waitcnt lgkmcnt(0)
	v_cvt_pk_bf16_f32 v9, v9, v10
	global_store_dword v[16:17], v9, off offset:2944
; __device__ __forceinline__ int crow(int r, int hi) { return (r & 3) + 8 * (r >> 2) + 4 * hi; }
; __device__ __forceinline__ void attn2_block(const Block2& B, char* lds) {
;     ...
;     for (int r = 0; r < 16; ++r) { const int orow = crow(r, hi);
; #pragma unroll
;         for (int d0 = 0; d0 < 4; ++d0) { const float v = o[d0][r] * rli[r]; const float vn = __shfl_xor(v, 1);
;             if ((r32 & 1) == 0) *(unsigned*)(Ow + (size_t)orow * D + d0 * 32 + r32) = cvtpk(v, vn); } }
.LBB0_472:
	s_or_b64 exec, exec, s[4:5]
	v_mul_f32_e32 v8, v119, v8
	s_nop 1
	v_mov_b32_dpp v9, v8 quad_perm:[1,0,3,2] row_mask:0xf bank_mask:0xf
	s_and_saveexec_b64 s[4:5], s[2:3]
	s_cbranch_execz .LBB0_474
	s_waitcnt lgkmcnt(0)
	v_cvt_pk_bf16_f32 v8, v8, v9
	global_store_dword v[16:17], v8, off offset:3008
.LBB0_474:
	s_or_b64 exec, exec, s[4:5]
	v_rcp_f32_e32 v4, v4
	s_nop 0
	v_mul_f32_e32 v8, v72, v4
	s_waitcnt lgkmcnt(0)
	s_nop 1
	v_mov_b32_dpp v9, v8 quad_perm:[1,0,3,2] row_mask:0xf bank_mask:0xf
	s_and_saveexec_b64 s[4:5], s[2:3]
	s_cbranch_execz .LBB0_476
	s_waitcnt lgkmcnt(0)
	v_cvt_pk_bf16_f32 v10, v8, v9
	v_add_co_u32_e32 v8, vcc, 0x1000, v16
	s_nop 1
	v_addc_co_u32_e32 v9, vcc, 0, v17, vcc
	global_store_dword v[8:9], v10, off
.LBB0_476:
	s_or_b64 exec, exec, s[4:5]
	v_mul_f32_e32 v8, v88, v4
	s_waitcnt lgkmcnt(0)
	s_nop 1
	v_mov_b32_dpp v9, v8 quad_perm:[1,0,3,2] row_mask:0xf bank_mask:0xf
	s_and_saveexec_b64 s[4:5], s[2:3]
	s_cbranch_execz .LBB0_478
	s_waitcnt lgkmcnt(0)
	v_cvt_pk_bf16_f32 v10, v8, v9
	v_add_co_u32_e32 v8, vcc, 0x1000, v16
	s_nop 1
	v_addc_co_u32_e32 v9, vcc, 0, v17, vcc
	global_store_dword v[8:9], v10, off offset:64
.LBB0_478:
	s_or_b64 exec, exec, s[4:5]
	v_mul_f32_e32 v8, v104, v4
	s_waitcnt lgkmcnt(0)
	s_nop 1
	v_mov_b32_dpp v9, v8 quad_perm:[1,0,3,2] row_mask:0xf bank_mask:0xf
	s_and_saveexec_b64 s[4:5], s[2:3]
	s_cbranch_execz .LBB0_480
	s_waitcnt lgkmcnt(0)
	v_cvt_pk_bf16_f32 v10, v8, v9
	v_add_co_u32_e32 v8, vcc, 0x1000, v16
	s_nop 1
	v_addc_co_u32_e32 v9, vcc, 0, v17, vcc
	global_store_dword v[8:9], v10, off offset:128
.LBB0_480:
	s_or_b64 exec, exec, s[4:5]
	v_mul_f32_e32 v4, v120, v4
	s_nop 1
	v_mov_b32_dpp v8, v4 quad_perm:[1,0,3,2] row_mask:0xf bank_mask:0xf
	s_and_saveexec_b64 s[4:5], s[2:3]
	s_cbranch_execz .LBB0_482
	s_waitcnt lgkmcnt(0)
	v_cvt_pk_bf16_f32 v4, v4, v8
	v_add_co_u32_e32 v8, vcc, 0x1000, v16
	s_nop 1
	v_addc_co_u32_e32 v9, vcc, 0, v17, vcc
	global_store_dword v[8:9], v4, off offset:192
.LBB0_482:
	s_or_b64 exec, exec, s[4:5]
	v_rcp_f32_e32 v4, v5
	s_nop 0
	v_mul_f32_e32 v5, v73, v4
	s_waitcnt lgkmcnt(0)
	s_nop 1
	v_mov_b32_dpp v8, v5 quad_perm:[1,0,3,2] row_mask:0xf bank_mask:0xf
	s_and_saveexec_b64 s[4:5], s[2:3]
	s_cbranch_execz .LBB0_484
	s_waitcnt lgkmcnt(0)
	v_cvt_pk_bf16_f32 v5, v5, v8
	v_add_co_u32_e32 v8, vcc, 0x1000, v16
	s_nop 1
	v_addc_co_u32_e32 v9, vcc, 0, v17, vcc
	global_store_dword v[8:9], v5, off offset:256
.LBB0_484:
	s_or_b64 exec, exec, s[4:5]
	v_mul_f32_e32 v5, v89, v4
	s_waitcnt lgkmcnt(0)
	s_nop 1
	v_mov_b32_dpp v8, v5 quad_perm:[1,0,3,2] row_mask:0xf bank_mask:0xf
	s_and_saveexec_b64 s[4:5], s[2:3]
	s_cbranch_execz .LBB0_486
	s_waitcnt lgkmcnt(0)
	v_cvt_pk_bf16_f32 v5, v5, v8
	v_add_co_u32_e32 v8, vcc, 0x1000, v16
	s_nop 1
	v_addc_co_u32_e32 v9, vcc, 0, v17, vcc
	global_store_dword v[8:9], v5, off offset:320
.LBB0_486:
	s_or_b64 exec, exec, s[4:5]
	v_mul_f32_e32 v5, v105, v4
	s_waitcnt lgkmcnt(0)
	s_nop 1
	v_mov_b32_dpp v8, v5 quad_perm:[1,0,3,2] row_mask:0xf bank_mask:0xf
	s_and_saveexec_b64 s[4:5], s[2:3]
	s_cbranch_execz .LBB0_488
	s_waitcnt lgkmcnt(0)
	v_cvt_pk_bf16_f32 v5, v5, v8
	v_add_co_u32_e32 v8, vcc, 0x1000, v16
	s_nop 1
	v_addc_co_u32_e32 v9, vcc, 0, v17, vcc
	global_store_dword v[8:9], v5, off offset:384
.LBB0_488:
	s_or_b64 exec, exec, s[4:5]
	v_mul_f32_e32 v4, v121, v4
	s_nop 1
	v_mov_b32_dpp v5, v4 quad_perm:[1,0,3,2] row_mask:0xf bank_mask:0xf
	s_and_saveexec_b64 s[4:5], s[2:3]
	s_cbranch_execz .LBB0_490
	s_waitcnt lgkmcnt(0)
	v_cvt_pk_bf16_f32 v8, v4, v5
	v_add_co_u32_e32 v4, vcc, 0x1000, v16
	s_nop 1
	v_addc_co_u32_e32 v5, vcc, 0, v17, vcc
	global_store_dword v[4:5], v8, off offset:448
.LBB0_490:
	s_or_b64 exec, exec, s[4:5]
	v_rcp_f32_e32 v4, v6
	s_waitcnt lgkmcnt(0)
	v_mul_f32_e32 v5, v74, v4
	s_nop 1
	v_mov_b32_dpp v6, v5 quad_perm:[1,0,3,2] row_mask:0xf bank_mask:0xf
	s_and_saveexec_b64 s[4:5], s[2:3]
	s_cbranch_execz .LBB0_492
	v_add_co_u32_e32 v8, vcc, 0x1000, v16
	s_waitcnt lgkmcnt(0)
	v_cvt_pk_bf16_f32 v5, v5, v6
	s_nop 0
	v_addc_co_u32_e32 v9, vcc, 0, v17, vcc
	global_store_dword v[8:9], v5, off offset:512
.LBB0_492:
	s_or_b64 exec, exec, s[4:5]
	v_mul_f32_e32 v5, v90, v4
	s_waitcnt lgkmcnt(0)
	s_nop 1
	v_mov_b32_dpp v6, v5 quad_perm:[1,0,3,2] row_mask:0xf bank_mask:0xf
	s_and_saveexec_b64 s[4:5], s[2:3]
	s_cbranch_execz .LBB0_494
	v_add_co_u32_e32 v8, vcc, 0x1000, v16
	s_waitcnt lgkmcnt(0)
	v_cvt_pk_bf16_f32 v5, v5, v6
	s_nop 0
	v_addc_co_u32_e32 v9, vcc, 0, v17, vcc
	global_store_dword v[8:9], v5, off offset:576
.LBB0_494:
	s_or_b64 exec, exec, s[4:5]
	v_mul_f32_e32 v5, v106, v4
	s_waitcnt lgkmcnt(0)
	s_nop 1
	v_mov_b32_dpp v6, v5 quad_perm:[1,0,3,2] row_mask:0xf bank_mask:0xf
	s_and_saveexec_b64 s[4:5], s[2:3]
	s_cbranch_execz .LBB0_496
	v_add_co_u32_e32 v8, vcc, 0x1000, v16
	s_waitcnt lgkmcnt(0)
	v_cvt_pk_bf16_f32 v5, v5, v6
	s_nop 0
	v_addc_co_u32_e32 v9, vcc, 0, v17, vcc
	global_store_dword v[8:9], v5, off offset:640
.LBB0_496:
	s_or_b64 exec, exec, s[4:5]
	v_mul_f32_e32 v4, v122, v4
	s_nop 1
	v_mov_b32_dpp v5, v4 quad_perm:[1,0,3,2] row_mask:0xf bank_mask:0xf
	s_and_saveexec_b64 s[4:5], s[2:3]
	s_cbranch_execz .LBB0_498
	s_waitcnt lgkmcnt(0)
	v_cvt_pk_bf16_f32 v6, v4, v5
	v_add_co_u32_e32 v4, vcc, 0x1000, v16
	s_nop 1
	v_addc_co_u32_e32 v5, vcc, 0, v17, vcc
	global_store_dword v[4:5], v6, off offset:704
.LBB0_498:
	s_or_b64 exec, exec, s[4:5]
	v_rcp_f32_e32 v4, v7
	s_waitcnt lgkmcnt(0)
	v_mul_f32_e32 v5, v75, v4
	s_nop 1
	v_mov_b32_dpp v6, v5 quad_perm:[1,0,3,2] row_mask:0xf bank_mask:0xf
	s_and_saveexec_b64 s[4:5], s[2:3]
	s_cbranch_execz .LBB0_500
	s_waitcnt lgkmcnt(0)
	v_cvt_pk_bf16_f32 v5, v5, v6
	v_add_co_u32_e32 v6, vcc, 0x1000, v16
	s_nop 1
	v_addc_co_u32_e32 v7, vcc, 0, v17, vcc
	global_store_dword v[6:7], v5, off offset:768
; __device__ __forceinline__ int crow(int r, int hi) { return (r & 3) + 8 * (r >> 2) + 4 * hi; }
; __device__ __forceinline__ void attn2_block(const Block2& B, char* lds) {
;     ...
;     for (int r = 0; r < 16; ++r) { const int orow = crow(r, hi);
; #pragma unroll
;         for (int d0 = 0; d0 < 4; ++d0) { const float v = o[d0][r] * rli[r]; const float vn = __shfl_xor(v, 1);
;             if ((r32 & 1) == 0) *(unsigned*)(Ow + (size_t)orow * D + d0 * 32 + r32) = cvtpk(v, vn); } }
.LBB0_500:
	s_or_b64 exec, exec, s[4:5]
	v_mul_f32_e32 v5, v91, v4
	s_waitcnt lgkmcnt(0)
	s_nop 1
	v_mov_b32_dpp v6, v5 quad_perm:[1,0,3,2] row_mask:0xf bank_mask:0xf
	s_and_saveexec_b64 s[4:5], s[2:3]
	s_cbranch_execz .LBB0_502
	s_waitcnt lgkmcnt(0)
	v_cvt_pk_bf16_f32 v5, v5, v6
	v_add_co_u32_e32 v6, vcc, 0x1000, v16
	s_nop 1
	v_addc_co_u32_e32 v7, vcc, 0, v17, vcc
	global_store_dword v[6:7], v5, off offset:832
.LBB0_502:
	s_or_b64 exec, exec, s[4:5]
	v_mul_f32_e32 v5, v107, v4
	s_waitcnt lgkmcnt(0)
	s_nop 1
	v_mov_b32_dpp v6, v5 quad_perm:[1,0,3,2] row_mask:0xf bank_mask:0xf
	s_and_saveexec_b64 s[4:5], s[2:3]
	s_cbranch_execz .LBB0_504
	s_waitcnt lgkmcnt(0)
	v_cvt_pk_bf16_f32 v5, v5, v6
	v_add_co_u32_e32 v6, vcc, 0x1000, v16
	s_nop 1
	v_addc_co_u32_e32 v7, vcc, 0, v17, vcc
	global_store_dword v[6:7], v5, off offset:896
.LBB0_504:
	s_or_b64 exec, exec, s[4:5]
	v_mul_f32_e32 v4, v123, v4
	s_nop 1
	v_mov_b32_dpp v5, v4 quad_perm:[1,0,3,2] row_mask:0xf bank_mask:0xf
	s_and_saveexec_b64 s[4:5], s[2:3]
	s_cbranch_execz .LBB0_506
	s_waitcnt lgkmcnt(0)
	v_cvt_pk_bf16_f32 v6, v4, v5
	v_add_co_u32_e32 v4, vcc, 0x1000, v16
	s_nop 1
	v_addc_co_u32_e32 v5, vcc, 0, v17, vcc
	global_store_dword v[4:5], v6, off offset:960
.LBB0_506:
	s_or_b64 exec, exec, s[4:5]
	v_rcp_f32_e32 v0, v0
	s_nop 0
	v_mul_f32_e32 v4, v76, v0
	s_waitcnt lgkmcnt(0)
	s_nop 1
	v_mov_b32_dpp v5, v4 quad_perm:[1,0,3,2] row_mask:0xf bank_mask:0xf
	s_and_saveexec_b64 s[4:5], s[2:3]
	s_cbranch_execz .LBB0_508
	s_waitcnt lgkmcnt(0)
	v_cvt_pk_bf16_f32 v6, v4, v5
	v_add_co_u32_e32 v4, vcc, 0x1000, v16
	s_nop 1
	v_addc_co_u32_e32 v5, vcc, 0, v17, vcc
	global_store_dword v[4:5], v6, off offset:2048
.LBB0_508:
	s_or_b64 exec, exec, s[4:5]
	v_mul_f32_e32 v4, v92, v0
	s_waitcnt lgkmcnt(0)
	s_nop 1
	v_mov_b32_dpp v5, v4 quad_perm:[1,0,3,2] row_mask:0xf bank_mask:0xf
	s_and_saveexec_b64 s[4:5], s[2:3]
	s_cbranch_execz .LBB0_510
	s_waitcnt lgkmcnt(0)
	v_cvt_pk_bf16_f32 v6, v4, v5
	v_add_co_u32_e32 v4, vcc, 0x1000, v16
	s_nop 1
	v_addc_co_u32_e32 v5, vcc, 0, v17, vcc
	global_store_dword v[4:5], v6, off offset:2112
.LBB0_510:
	s_or_b64 exec, exec, s[4:5]
	v_mul_f32_e32 v4, v108, v0
	s_waitcnt lgkmcnt(0)
	s_nop 1
	v_mov_b32_dpp v5, v4 quad_perm:[1,0,3,2] row_mask:0xf bank_mask:0xf
	s_and_saveexec_b64 s[4:5], s[2:3]
	s_cbranch_execz .LBB0_512
	s_waitcnt lgkmcnt(0)
	v_cvt_pk_bf16_f32 v6, v4, v5
	v_add_co_u32_e32 v4, vcc, 0x1000, v16
	s_nop 1
	v_addc_co_u32_e32 v5, vcc, 0, v17, vcc
	global_store_dword v[4:5], v6, off offset:2176
.LBB0_512:
	s_or_b64 exec, exec, s[4:5]
	v_mul_f32_e32 v0, v124, v0
	s_nop 1
	v_mov_b32_dpp v4, v0 quad_perm:[1,0,3,2] row_mask:0xf bank_mask:0xf
	s_and_saveexec_b64 s[4:5], s[2:3]
	s_cbranch_execz .LBB0_514
	s_waitcnt lgkmcnt(0)
	v_cvt_pk_bf16_f32 v0, v0, v4
	v_add_co_u32_e32 v4, vcc, 0x1000, v16
	s_nop 1
	v_addc_co_u32_e32 v5, vcc, 0, v17, vcc
	global_store_dword v[4:5], v0, off offset:2240
.LBB0_514:
	s_or_b64 exec, exec, s[4:5]
	v_rcp_f32_e32 v0, v1
	s_nop 0
	v_mul_f32_e32 v1, v77, v0
	s_waitcnt lgkmcnt(0)
	s_nop 1
	v_mov_b32_dpp v4, v1 quad_perm:[1,0,3,2] row_mask:0xf bank_mask:0xf
	s_and_saveexec_b64 s[4:5], s[2:3]
	s_cbranch_execz .LBB0_516
	s_waitcnt lgkmcnt(0)
	v_cvt_pk_bf16_f32 v1, v1, v4
	v_add_co_u32_e32 v4, vcc, 0x1000, v16
	s_nop 1
	v_addc_co_u32_e32 v5, vcc, 0, v17, vcc
	global_store_dword v[4:5], v1, off offset:2304
.LBB0_516:
	s_or_b64 exec, exec, s[4:5]
	v_mul_f32_e32 v1, v93, v0
	s_waitcnt lgkmcnt(0)
	s_nop 1
	v_mov_b32_dpp v4, v1 quad_perm:[1,0,3,2] row_mask:0xf bank_mask:0xf
	s_and_saveexec_b64 s[4:5], s[2:3]
	s_cbranch_execz .LBB0_518
	s_waitcnt lgkmcnt(0)
	v_cvt_pk_bf16_f32 v1, v1, v4
	v_add_co_u32_e32 v4, vcc, 0x1000, v16
	s_nop 1
	v_addc_co_u32_e32 v5, vcc, 0, v17, vcc
	global_store_dword v[4:5], v1, off offset:2368
; __device__ __forceinline__ int crow(int r, int hi) { return (r & 3) + 8 * (r >> 2) + 4 * hi; }
; __device__ __forceinline__ void attn2_block(const Block2& B, char* lds) {
;     ...
;     for (int r = 0; r < 16; ++r) { const int orow = crow(r, hi);
; #pragma unroll
;         for (int d0 = 0; d0 < 4; ++d0) { const float v = o[d0][r] * rli[r]; const float vn = __shfl_xor(v, 1);
;             if ((r32 & 1) == 0) *(unsigned*)(Ow + (size_t)orow * D + d0 * 32 + r32) = cvtpk(v, vn); } }
.LBB0_518:
	s_or_b64 exec, exec, s[4:5]
	v_mul_f32_e32 v1, v109, v0
	s_waitcnt lgkmcnt(0)
	s_nop 1
	v_mov_b32_dpp v4, v1 quad_perm:[1,0,3,2] row_mask:0xf bank_mask:0xf
	s_and_saveexec_b64 s[4:5], s[2:3]
	s_cbranch_execz .LBB0_520
	s_waitcnt lgkmcnt(0)
	v_cvt_pk_bf16_f32 v1, v1, v4
	v_add_co_u32_e32 v4, vcc, 0x1000, v16
	s_nop 1
	v_addc_co_u32_e32 v5, vcc, 0, v17, vcc
	global_store_dword v[4:5], v1, off offset:2432
.LBB0_520:
	s_or_b64 exec, exec, s[4:5]
	v_mul_f32_e32 v0, v125, v0
	s_nop 1
	v_mov_b32_dpp v1, v0 quad_perm:[1,0,3,2] row_mask:0xf bank_mask:0xf
	s_and_saveexec_b64 s[4:5], s[2:3]
	s_cbranch_execz .LBB0_522
	s_waitcnt lgkmcnt(0)
	v_cvt_pk_bf16_f32 v4, v0, v1
	v_add_co_u32_e32 v0, vcc, 0x1000, v16
	s_nop 1
	v_addc_co_u32_e32 v1, vcc, 0, v17, vcc
	global_store_dword v[0:1], v4, off offset:2496
.LBB0_522:
	s_or_b64 exec, exec, s[4:5]
	v_rcp_f32_e32 v0, v2
	s_waitcnt lgkmcnt(0)
	v_mul_f32_e32 v1, v78, v0
	s_nop 1
	v_mov_b32_dpp v2, v1 quad_perm:[1,0,3,2] row_mask:0xf bank_mask:0xf
	s_and_saveexec_b64 s[4:5], s[2:3]
	s_cbranch_execz .LBB0_524
	v_add_co_u32_e32 v4, vcc, 0x1000, v16
	s_waitcnt lgkmcnt(0)
	v_cvt_pk_bf16_f32 v1, v1, v2
	s_nop 0
	v_addc_co_u32_e32 v5, vcc, 0, v17, vcc
	global_store_dword v[4:5], v1, off offset:2560
.LBB0_524:
	s_or_b64 exec, exec, s[4:5]
	v_mul_f32_e32 v1, v94, v0
	s_waitcnt lgkmcnt(0)
	s_nop 1
	v_mov_b32_dpp v2, v1 quad_perm:[1,0,3,2] row_mask:0xf bank_mask:0xf
	s_and_saveexec_b64 s[4:5], s[2:3]
	s_cbranch_execz .LBB0_526
	v_add_co_u32_e32 v4, vcc, 0x1000, v16
	s_waitcnt lgkmcnt(0)
	v_cvt_pk_bf16_f32 v1, v1, v2
	s_nop 0
	v_addc_co_u32_e32 v5, vcc, 0, v17, vcc
	global_store_dword v[4:5], v1, off offset:2624
.LBB0_526:
	s_or_b64 exec, exec, s[4:5]
	v_mul_f32_e32 v1, v110, v0
	s_waitcnt lgkmcnt(0)
	s_nop 1
	v_mov_b32_dpp v2, v1 quad_perm:[1,0,3,2] row_mask:0xf bank_mask:0xf
	s_and_saveexec_b64 s[4:5], s[2:3]
	s_cbranch_execz .LBB0_528
	v_add_co_u32_e32 v4, vcc, 0x1000, v16
	s_waitcnt lgkmcnt(0)
	v_cvt_pk_bf16_f32 v1, v1, v2
	s_nop 0
	v_addc_co_u32_e32 v5, vcc, 0, v17, vcc
	global_store_dword v[4:5], v1, off offset:2688
.LBB0_528:
	s_or_b64 exec, exec, s[4:5]
	v_mul_f32_e32 v0, v126, v0
	s_nop 1
	v_mov_b32_dpp v1, v0 quad_perm:[1,0,3,2] row_mask:0xf bank_mask:0xf
	s_and_saveexec_b64 s[4:5], s[2:3]
	s_cbranch_execz .LBB0_530
	s_waitcnt lgkmcnt(0)
	v_cvt_pk_bf16_f32 v2, v0, v1
	v_add_co_u32_e32 v0, vcc, 0x1000, v16
	s_nop 1
	v_addc_co_u32_e32 v1, vcc, 0, v17, vcc
	global_store_dword v[0:1], v2, off offset:2752
.LBB0_530:
	s_or_b64 exec, exec, s[4:5]
	v_rcp_f32_e32 v0, v3
	s_waitcnt lgkmcnt(0)
	v_mul_f32_e32 v1, v79, v0
	s_nop 1
	v_mov_b32_dpp v2, v1 quad_perm:[1,0,3,2] row_mask:0xf bank_mask:0xf
	s_and_saveexec_b64 s[4:5], s[2:3]
	s_cbranch_execz .LBB0_532
	s_waitcnt lgkmcnt(0)
	v_cvt_pk_bf16_f32 v1, v1, v2
	v_add_co_u32_e32 v2, vcc, 0x1000, v16
	s_nop 1
	v_addc_co_u32_e32 v3, vcc, 0, v17, vcc
	global_store_dword v[2:3], v1, off offset:2816
.LBB0_532:
	s_or_b64 exec, exec, s[4:5]
	v_mul_f32_e32 v1, v95, v0
	s_waitcnt lgkmcnt(0)
	s_nop 1
	v_mov_b32_dpp v2, v1 quad_perm:[1,0,3,2] row_mask:0xf bank_mask:0xf
	s_and_saveexec_b64 s[4:5], s[2:3]
	s_cbranch_execz .LBB0_534
	s_waitcnt lgkmcnt(0)
	v_cvt_pk_bf16_f32 v1, v1, v2
	v_add_co_u32_e32 v2, vcc, 0x1000, v16
	s_nop 1
	v_addc_co_u32_e32 v3, vcc, 0, v17, vcc
	global_store_dword v[2:3], v1, off offset:2880
.LBB0_534:
	s_or_b64 exec, exec, s[4:5]
	v_mul_f32_e32 v1, v111, v0
	s_waitcnt lgkmcnt(0)
	s_nop 1
	v_mov_b32_dpp v2, v1 quad_perm:[1,0,3,2] row_mask:0xf bank_mask:0xf
	s_and_saveexec_b64 s[4:5], s[2:3]
	s_cbranch_execz .LBB0_536
	s_waitcnt lgkmcnt(0)
	v_cvt_pk_bf16_f32 v1, v1, v2
	v_add_co_u32_e32 v2, vcc, 0x1000, v16
	s_nop 1
	v_addc_co_u32_e32 v3, vcc, 0, v17, vcc
	global_store_dword v[2:3], v1, off offset:2944
.LBB0_536:
	s_or_b64 exec, exec, s[4:5]
	v_mul_f32_e32 v0, v127, v0
	s_nop 1
	v_mov_b32_dpp v1, v0 quad_perm:[1,0,3,2] row_mask:0xf bank_mask:0xf
	s_and_saveexec_b64 s[4:5], s[2:3]
	s_cbranch_execz .LBB0_341
	s_waitcnt lgkmcnt(0)
	v_cvt_pk_bf16_f32 v2, v0, v1
	v_add_co_u32_e32 v0, vcc, 0x1000, v16
	s_nop 1
	v_addc_co_u32_e32 v1, vcc, 0, v17, vcc
	global_store_dword v[0:1], v2, off offset:3008
	s_branch .LBB0_341
